# plus P5: first-tile loads of the YA@Wba GEMM issued before the sigmoid gate epilogue
# speedup vs baseline: 1.0274x; 1.0006x over previous
;     ...
;   const int srow = tid >> 3, scol = (tid & 7) * 8;
;   const u16* ap = A + (size_t)srow * lda + scol;
;   const u16* bp = B + (size_t)srow * ldb + scol;
;   bf16x8 ra[DEPTH][4], rb[DEPTH][4];
;   float ssq[4] = {0.f, 0.f, 0.f, 0.f};
;   const int nk = K >> 6;
; #pragma unroll
;   for (int d = 0; d < DEPTH; ++d)
; #pragma unroll
;     for (int i = 0; i < 4; ++i) {
;       ra[d][i] = *(const bf16x8*)(ap + d * 64 + (size_t)(32 * i) * lda);
;       rb[d][i] = *(const bf16x8*)(bp + d * 64 + (size_t)(32 * i) * ldb);
;     }
; DEV void gemm_gates(f32x16 (&acc)[2][4], const u16* __restrict__ A, const u16* __restrict__ B0, const u16* __restrict__ B1,
;                     unsigned char* smem) {
;     ...
;     for (int ks = 0; ks < 4; ++ks) {
;       bf16x8 af[2], bfr[4];
; #pragma unroll
;       for (int i = 0; i < 2; ++i) af[i] = *(const bf16x8*)(sA + (wm * 64 + i * 32) * LDT + fro + ks * 16);
; #pragma unroll
;       for (int i = 0; i < 4; ++i)
;         bfr[i] = *(const bf16x8*)(sB + ((i >> 1) * 128 + wn * 64 + (i & 1) * 32) * LDT + fro + ks * 16);
;       __builtin_amdgcn_s_setprio(1);
; #pragma unroll
;       for (int mi = 0; mi < 2; ++mi)
; #pragma unroll
;         for (int ni = 0; ni < 4; ++ni)
;           acc[mi][ni] = __builtin_amdgcn_mfma_f32_32x32x16_bf16(af[mi], bfr[ni], acc[mi][ni], 0, 0, 0);
;       __builtin_amdgcn_s_setprio(0);
;     }
;   }
;   __syncthreads();
.LBB0_1309:
	v_add_u32_e32 v210, s36, v183
	v_add_u32_e32 v211, s36, v184
	ds_read_b128 v[186:189], v210
	ds_read_b128 v[190:193], v210 offset:4608
	ds_read_b128 v[194:197], v211
	ds_read_b128 v[198:201], v211 offset:4608
	ds_read_b128 v[202:205], v211 offset:18432
	ds_read_b128 v[206:209], v211 offset:23040
	s_setprio 1
	s_waitcnt lgkmcnt(3)
	v_mfma_f32_32x32x16_bf16 v[48:63], v[186:189], v[194:197], v[48:63]
	s_waitcnt lgkmcnt(2)
	v_mfma_f32_32x32x16_bf16 v[32:47], v[186:189], v[198:201], v[32:47]
	s_waitcnt lgkmcnt(1)
	v_mfma_f32_32x32x16_bf16 v[112:127], v[186:189], v[202:205], v[112:127]
	s_waitcnt lgkmcnt(0)
	v_mfma_f32_32x32x16_bf16 v[96:111], v[186:189], v[206:209], v[96:111]
	v_mfma_f32_32x32x16_bf16 v[16:31], v[190:193], v[194:197], v[16:31]
	v_mfma_f32_32x32x16_bf16 v[0:15], v[190:193], v[198:201], v[0:15]
	v_mfma_f32_32x32x16_bf16 v[80:95], v[190:193], v[202:205], v[80:95]
	v_mfma_f32_32x32x16_bf16 v[64:79], v[190:193], v[206:209], v[64:79]
	s_setprio 0
	ds_read_b128 v[186:189], v210 offset:32
	ds_read_b128 v[190:193], v210 offset:4640
	ds_read_b128 v[194:197], v211 offset:32
	ds_read_b128 v[198:201], v211 offset:4640
	ds_read_b128 v[202:205], v211 offset:18464
	ds_read_b128 v[206:209], v211 offset:23072
	s_setprio 1
	s_waitcnt lgkmcnt(3)
	v_mfma_f32_32x32x16_bf16 v[48:63], v[186:189], v[194:197], v[48:63]
	s_waitcnt lgkmcnt(2)
	v_mfma_f32_32x32x16_bf16 v[32:47], v[186:189], v[198:201], v[32:47]
	s_waitcnt lgkmcnt(1)
	v_mfma_f32_32x32x16_bf16 v[112:127], v[186:189], v[202:205], v[112:127]
	s_waitcnt lgkmcnt(0)
	v_mfma_f32_32x32x16_bf16 v[96:111], v[186:189], v[206:209], v[96:111]
	v_mfma_f32_32x32x16_bf16 v[16:31], v[190:193], v[194:197], v[16:31]
	v_mfma_f32_32x32x16_bf16 v[0:15], v[190:193], v[198:201], v[0:15]
	v_mfma_f32_32x32x16_bf16 v[80:95], v[190:193], v[202:205], v[80:95]
	v_mfma_f32_32x32x16_bf16 v[64:79], v[190:193], v[206:209], v[64:79]
	s_setprio 0
	s_add_i32 s36, s36, 64
	s_cmpk_eq_i32 s36, 0x80
	s_cbranch_scc0 .LBB0_1309
	s_add_i32 s21, s21, 1
	s_cmp_eq_u32 s21, 16
	s_cbranch_scc0 .LBB0_1306
	v_mul_f32_e32 v112, 0xbfb8aa3b, v112
	v_mul_f32_e32 v113, 0xbfb8aa3b, v113
	v_exp_f32_e32 v112, v112
	v_exp_f32_e32 v113, v113
	v_lshlrev_b32_e32 v248, 2, v182
	s_barrier
	s_lshl_b64 s[36:37], s[0:1], 1
	s_add_u32 s36, s8, s36
	s_addc_u32 s37, s9, s37
	s_lshl_b32 s38, s20, 1
	s_add_u32 s38, s14, s38
	s_addc_u32 s39, s15, 0
	v_ashrrev_i32_e32 v216, 3, v232
	v_ashrrev_i32_e32 v217, 31, v216
	v_lshlrev_b64 v[216:217], 11, v[216:217]
	v_lshlrev_b32_e32 v218, 4, v232
	v_and_b32_e32 v218, 0x70, v218
	v_mov_b32_e32 v219, 0
	v_lshl_add_u64 v[220:221], s[36:37], 0, v[216:217]
	v_lshl_add_u64 v[220:221], v[220:221], 0, v[218:219]
	v_lshl_add_u64 v[222:223], s[38:39], 0, v[216:217]
	v_lshl_add_u64 v[222:223], v[222:223], 0, v[218:219]
	global_load_dwordx4 v[184:187], v[220:221], off
	global_load_dwordx4 v[188:191], v[222:223], off
	v_add_co_u32_e32 v216, vcc, s35, v220
	s_nop 1
	v_addc_co_u32_e32 v217, vcc, 0, v221, vcc
	global_load_dwordx4 v[192:195], v[216:217], off
	v_add_co_u32_e32 v218, vcc, s35, v222
	s_nop 1
	v_addc_co_u32_e32 v219, vcc, 0, v223, vcc
	global_load_dwordx4 v[196:199], v[218:219], off
	v_add_co_u32_e32 v216, vcc, s33, v220
	s_nop 1
	v_addc_co_u32_e32 v217, vcc, 0, v221, vcc
	global_load_dwordx4 v[200:203], v[216:217], off
	v_add_co_u32_e32 v218, vcc, s33, v222
	s_nop 1
	v_addc_co_u32_e32 v219, vcc, 0, v223, vcc
	global_load_dwordx4 v[204:207], v[218:219], off
	v_add_co_u32_e32 v216, vcc, s40, v220
	s_nop 1
	v_addc_co_u32_e32 v217, vcc, 0, v221, vcc
	global_load_dwordx4 v[208:211], v[216:217], off
	v_add_co_u32_e32 v218, vcc, s40, v222
	s_nop 1
	v_addc_co_u32_e32 v219, vcc, 0, v223, vcc
	global_load_dwordx4 v[212:215], v[218:219], off
	v_pk_add_f32 v[112:113], v[112:113], 1.0 op_sel_hi:[1,0]
	s_waitcnt vmcnt(10)
	v_div_scale_f32 v128, s[36:37], v113, v113, 1.0
	v_rcp_f32_e32 v129, v128
	v_add_u32_e32 v249, 0x9400, v248
	v_fma_f32 v130, -v128, v129, 1.0
	v_fmac_f32_e32 v129, v130, v129
	v_div_scale_f32 v130, vcc, 1.0, v113, 1.0
	v_mul_f32_e32 v131, v130, v129
	s_waitcnt vmcnt(9)
	v_fma_f32 v132, -v128, v131, v130
	v_fmac_f32_e32 v131, v132, v129
	v_fma_f32 v128, -v128, v131, v130
	v_div_fmas_f32 v128, v128, v129, v131
	v_div_fixup_f32 v113, v128, v113, 1.0
	v_div_scale_f32 v128, s[36:37], v112, v112, 1.0
	v_rcp_f32_e32 v129, v128
	s_nop 0
	v_fma_f32 v130, -v128, v129, 1.0
	v_fmac_f32_e32 v129, v130, v129
	v_div_scale_f32 v130, vcc, 1.0, v112, 1.0
	v_mul_f32_e32 v131, v130, v129
	v_fma_f32 v132, -v128, v131, v130
	v_fmac_f32_e32 v131, v132, v129
	v_fma_f32 v128, -v128, v131, v130
	v_div_fmas_f32 v128, v128, v129, v131
	v_div_fixup_f32 v112, v128, v112, 1.0
	v_cvt_pk_bf16_f32 v128, v112, v113
	v_mul_f32_e32 v112, 0xbfb8aa3b, v114
	v_mul_f32_e32 v113, 0xbfb8aa3b, v115
	v_exp_f32_e32 v112, v112
	v_exp_f32_e32 v113, v113
	s_nop 0
	v_pk_add_f32 v[112:113], v[112:113], 1.0 op_sel_hi:[1,0]
	s_nop 0
	v_div_scale_f32 v114, s[36:37], v113, v113, 1.0
	v_rcp_f32_e32 v115, v114
	s_nop 0
	v_fma_f32 v129, -v114, v115, 1.0
	v_fmac_f32_e32 v115, v129, v115
	v_div_scale_f32 v129, vcc, 1.0, v113, 1.0
	v_mul_f32_e32 v130, v129, v115
	v_fma_f32 v131, -v114, v130, v129
	v_fmac_f32_e32 v130, v131, v115
	v_fma_f32 v114, -v114, v130, v129
	v_div_fmas_f32 v114, v114, v115, v130
	v_div_fixup_f32 v113, v114, v113, 1.0
	v_div_scale_f32 v114, s[36:37], v112, v112, 1.0
	v_rcp_f32_e32 v115, v114
	s_nop 0
	v_fma_f32 v129, -v114, v115, 1.0
	v_fmac_f32_e32 v115, v129, v115
	v_div_scale_f32 v129, vcc, 1.0, v112, 1.0
	v_mul_f32_e32 v130, v129, v115
	v_fma_f32 v131, -v114, v130, v129
	v_fmac_f32_e32 v130, v131, v115
	v_fma_f32 v114, -v114, v130, v129
; DEV float sigmoidf_(float x) { return 1.0f / (1.0f + __expf(-x)); }
; DEV void phase_p5(const Params& p, int l, unsigned char* smem) {
;     ...
; #pragma unroll
;       for (int a_ = 0; a_ < 2; ++a_)
; #pragma unroll
;         for (int b_ = 0; b_ < 2; ++b_) {
; #pragma unroll
;           for (int r = 0; r < 8; ++r)
;             sG[((a_ * 2 + b_) * 8 + r) * 256 + tid] = pk2bf(sigmoidf_(g[a_][2 + b_][2 * r]), sigmoidf_(g[a_][2 + b_][2 * r + 1]));
;           __builtin_amdgcn_sched_barrier(0);
;         }
	v_div_fmas_f32 v114, v114, v115, v130
	v_div_fixup_f32 v112, v114, v112, 1.0
	v_cvt_pk_bf16_f32 v112, v112, v113
	ds_write2st64_b32 v248, v128, v112 offset0:148 offset1:152
	v_mul_f32_e32 v112, 0xbfb8aa3b, v116
	v_mul_f32_e32 v113, 0xbfb8aa3b, v117
	v_exp_f32_e32 v112, v112
	v_exp_f32_e32 v113, v113
	s_nop 0
	v_pk_add_f32 v[112:113], v[112:113], 1.0 op_sel_hi:[1,0]
	s_nop 0
	v_div_scale_f32 v114, s[36:37], v113, v113, 1.0
	v_rcp_f32_e32 v115, v114
	s_nop 0
	v_fma_f32 v116, -v114, v115, 1.0
	v_fmac_f32_e32 v115, v116, v115
	v_div_scale_f32 v116, vcc, 1.0, v113, 1.0
	v_mul_f32_e32 v117, v116, v115
	v_fma_f32 v128, -v114, v117, v116
	v_fmac_f32_e32 v117, v128, v115
	v_fma_f32 v114, -v114, v117, v116
	v_div_fmas_f32 v114, v114, v115, v117
	v_div_fixup_f32 v113, v114, v113, 1.0
	v_div_scale_f32 v114, s[36:37], v112, v112, 1.0
	v_rcp_f32_e32 v115, v114
	s_nop 0
	v_fma_f32 v116, -v114, v115, 1.0
	v_fmac_f32_e32 v115, v116, v115
	v_div_scale_f32 v116, vcc, 1.0, v112, 1.0
	v_mul_f32_e32 v117, v116, v115
	v_fma_f32 v128, -v114, v117, v116
	v_fmac_f32_e32 v117, v128, v115
	v_fma_f32 v114, -v114, v117, v116
	v_div_fmas_f32 v114, v114, v115, v117
	v_div_fixup_f32 v112, v114, v112, 1.0
	v_cvt_pk_bf16_f32 v114, v112, v113
	v_mul_f32_e32 v112, 0xbfb8aa3b, v118
	v_mul_f32_e32 v113, 0xbfb8aa3b, v119
	v_exp_f32_e32 v112, v112
	v_exp_f32_e32 v113, v113
	s_nop 0
	v_pk_add_f32 v[112:113], v[112:113], 1.0 op_sel_hi:[1,0]
	s_nop 0
	v_div_scale_f32 v115, s[36:37], v113, v113, 1.0
	v_rcp_f32_e32 v116, v115
	s_nop 0
	v_fma_f32 v117, -v115, v116, 1.0
	v_fmac_f32_e32 v116, v117, v116
	v_div_scale_f32 v117, vcc, 1.0, v113, 1.0
	v_mul_f32_e32 v118, v117, v116
	v_fma_f32 v119, -v115, v118, v117
	v_fmac_f32_e32 v118, v119, v116
	v_fma_f32 v115, -v115, v118, v117
	v_div_fmas_f32 v115, v115, v116, v118
	v_div_fixup_f32 v113, v115, v113, 1.0
	v_div_scale_f32 v115, s[36:37], v112, v112, 1.0
	v_rcp_f32_e32 v116, v115
	s_nop 0
	v_fma_f32 v117, -v115, v116, 1.0
	v_fmac_f32_e32 v116, v117, v116
	v_div_scale_f32 v117, vcc, 1.0, v112, 1.0
	v_mul_f32_e32 v118, v117, v116
	v_fma_f32 v119, -v115, v118, v117
	v_fmac_f32_e32 v118, v119, v116
	v_fma_f32 v115, -v115, v118, v117
	v_div_fmas_f32 v115, v115, v116, v118
	v_div_fixup_f32 v112, v115, v112, 1.0
	v_cvt_pk_bf16_f32 v112, v112, v113
	ds_write2st64_b32 v248, v114, v112 offset0:156 offset1:160
	v_mul_f32_e32 v112, 0xbfb8aa3b, v120
	v_mul_f32_e32 v113, 0xbfb8aa3b, v121
	v_exp_f32_e32 v112, v112
	v_exp_f32_e32 v113, v113
	s_nop 0
	v_pk_add_f32 v[112:113], v[112:113], 1.0 op_sel_hi:[1,0]
	s_nop 0
	v_div_scale_f32 v114, s[36:37], v113, v113, 1.0
	v_rcp_f32_e32 v115, v114
	s_nop 0
	v_fma_f32 v116, -v114, v115, 1.0
	v_fmac_f32_e32 v115, v116, v115
	v_div_scale_f32 v116, vcc, 1.0, v113, 1.0
	v_mul_f32_e32 v117, v116, v115
	v_fma_f32 v118, -v114, v117, v116
	v_fmac_f32_e32 v117, v118, v115
	v_fma_f32 v114, -v114, v117, v116
	v_div_fmas_f32 v114, v114, v115, v117
	v_div_fixup_f32 v113, v114, v113, 1.0
	v_div_scale_f32 v114, s[36:37], v112, v112, 1.0
	v_rcp_f32_e32 v115, v114
	s_nop 0
	v_fma_f32 v116, -v114, v115, 1.0
	v_fmac_f32_e32 v115, v116, v115
	v_div_scale_f32 v116, vcc, 1.0, v112, 1.0
	v_mul_f32_e32 v117, v116, v115
	v_fma_f32 v118, -v114, v117, v116
	v_fmac_f32_e32 v117, v118, v115
	v_fma_f32 v114, -v114, v117, v116
	v_div_fmas_f32 v114, v114, v115, v117
	v_div_fixup_f32 v112, v114, v112, 1.0
	v_cvt_pk_bf16_f32 v114, v112, v113
	v_mul_f32_e32 v112, 0xbfb8aa3b, v122
	v_mul_f32_e32 v113, 0xbfb8aa3b, v123
	v_exp_f32_e32 v112, v112
	v_exp_f32_e32 v113, v113
	s_nop 0
	v_pk_add_f32 v[112:113], v[112:113], 1.0 op_sel_hi:[1,0]
	s_nop 0
	v_div_scale_f32 v115, s[36:37], v113, v113, 1.0
	v_rcp_f32_e32 v116, v115
	s_nop 0
	v_fma_f32 v117, -v115, v116, 1.0
	v_fmac_f32_e32 v116, v117, v116
	v_div_scale_f32 v117, vcc, 1.0, v113, 1.0
	v_mul_f32_e32 v118, v117, v116
	v_fma_f32 v119, -v115, v118, v117
	v_fmac_f32_e32 v118, v119, v116
	v_fma_f32 v115, -v115, v118, v117
	v_div_fmas_f32 v115, v115, v116, v118
	v_div_fixup_f32 v113, v115, v113, 1.0
	v_div_scale_f32 v115, s[36:37], v112, v112, 1.0
	v_rcp_f32_e32 v116, v115
	s_nop 0
	v_fma_f32 v117, -v115, v116, 1.0
	v_fmac_f32_e32 v116, v117, v116
	v_div_scale_f32 v117, vcc, 1.0, v112, 1.0
	v_mul_f32_e32 v118, v117, v116
	v_fma_f32 v119, -v115, v118, v117
	v_fmac_f32_e32 v118, v119, v116
	v_fma_f32 v115, -v115, v118, v117
	v_div_fmas_f32 v115, v115, v116, v118
	v_div_fixup_f32 v112, v115, v112, 1.0
	v_cvt_pk_bf16_f32 v112, v112, v113
	ds_write2st64_b32 v248, v114, v112 offset0:164 offset1:168
	v_mul_f32_e32 v112, 0xbfb8aa3b, v124
	v_mul_f32_e32 v113, 0xbfb8aa3b, v125
	v_exp_f32_e32 v112, v112
	v_exp_f32_e32 v113, v113
	s_nop 0
	v_pk_add_f32 v[112:113], v[112:113], 1.0 op_sel_hi:[1,0]
	s_nop 0
	v_div_scale_f32 v114, s[36:37], v113, v113, 1.0
	v_rcp_f32_e32 v115, v114
	s_nop 0
	v_fma_f32 v116, -v114, v115, 1.0
	v_fmac_f32_e32 v115, v116, v115
	v_div_scale_f32 v116, vcc, 1.0, v113, 1.0
	v_mul_f32_e32 v117, v116, v115
	v_fma_f32 v118, -v114, v117, v116
	v_fmac_f32_e32 v117, v118, v115
	v_fma_f32 v114, -v114, v117, v116
	v_div_fmas_f32 v114, v114, v115, v117
	v_div_fixup_f32 v113, v114, v113, 1.0
	v_div_scale_f32 v114, s[36:37], v112, v112, 1.0
	v_rcp_f32_e32 v115, v114
	s_nop 0
	v_fma_f32 v116, -v114, v115, 1.0
	v_fmac_f32_e32 v115, v116, v115
	v_div_scale_f32 v116, vcc, 1.0, v112, 1.0
	v_mul_f32_e32 v117, v116, v115
	v_fma_f32 v118, -v114, v117, v116
	v_fmac_f32_e32 v117, v118, v115
	v_fma_f32 v114, -v114, v117, v116
	v_div_fmas_f32 v114, v114, v115, v117
	v_div_fixup_f32 v112, v114, v112, 1.0
	v_cvt_pk_bf16_f32 v114, v112, v113
	v_mul_f32_e32 v112, 0xbfb8aa3b, v126
	v_mul_f32_e32 v113, 0xbfb8aa3b, v127
; DEV float sigmoidf_(float x) { return 1.0f / (1.0f + __expf(-x)); }
; DEV void phase_p5(const Params& p, int l, unsigned char* smem) {
;     ...
; #pragma unroll
;       for (int a_ = 0; a_ < 2; ++a_)
; #pragma unroll
;         for (int b_ = 0; b_ < 2; ++b_) {
; #pragma unroll
;           for (int r = 0; r < 8; ++r)
;             sG[((a_ * 2 + b_) * 8 + r) * 256 + tid] = pk2bf(sigmoidf_(g[a_][2 + b_][2 * r]), sigmoidf_(g[a_][2 + b_][2 * r + 1]));
;           __builtin_amdgcn_sched_barrier(0);
;         }
	v_exp_f32_e32 v112, v112
	v_exp_f32_e32 v113, v113
	s_nop 0
	v_pk_add_f32 v[112:113], v[112:113], 1.0 op_sel_hi:[1,0]
	s_nop 0
	v_div_scale_f32 v115, s[36:37], v113, v113, 1.0
	v_rcp_f32_e32 v116, v115
	s_nop 0
	v_fma_f32 v117, -v115, v116, 1.0
	v_fmac_f32_e32 v116, v117, v116
	v_div_scale_f32 v117, vcc, 1.0, v113, 1.0
	v_mul_f32_e32 v118, v117, v116
	v_fma_f32 v119, -v115, v118, v117
	v_fmac_f32_e32 v118, v119, v116
	v_fma_f32 v115, -v115, v118, v117
	v_div_fmas_f32 v115, v115, v116, v118
	v_div_fixup_f32 v113, v115, v113, 1.0
	v_div_scale_f32 v115, s[36:37], v112, v112, 1.0
	v_rcp_f32_e32 v116, v115
	s_nop 0
	v_fma_f32 v117, -v115, v116, 1.0
	v_fmac_f32_e32 v116, v117, v116
	v_div_scale_f32 v117, vcc, 1.0, v112, 1.0
	v_mul_f32_e32 v118, v117, v116
	v_fma_f32 v119, -v115, v118, v117
	v_fmac_f32_e32 v118, v119, v116
	v_fma_f32 v115, -v115, v118, v117
	v_div_fmas_f32 v115, v115, v116, v118
	v_div_fixup_f32 v112, v115, v112, 1.0
	v_cvt_pk_bf16_f32 v112, v112, v113
	ds_write2st64_b32 v248, v114, v112 offset0:172 offset1:176
	v_mul_f32_e32 v96, 0xbfb8aa3b, v96
	v_mul_f32_e32 v97, 0xbfb8aa3b, v97
	v_exp_f32_e32 v96, v96
	v_exp_f32_e32 v97, v97
	s_nop 0
	v_pk_add_f32 v[96:97], v[96:97], 1.0 op_sel_hi:[1,0]
	s_nop 0
	v_div_scale_f32 v112, s[36:37], v97, v97, 1.0
	v_rcp_f32_e32 v113, v112
	s_nop 0
	v_fma_f32 v114, -v112, v113, 1.0
	v_fmac_f32_e32 v113, v114, v113
	v_div_scale_f32 v114, vcc, 1.0, v97, 1.0
	v_mul_f32_e32 v115, v114, v113
	v_fma_f32 v116, -v112, v115, v114
	v_fmac_f32_e32 v115, v116, v113
	v_fma_f32 v112, -v112, v115, v114
	v_div_fmas_f32 v112, v112, v113, v115
	v_div_fixup_f32 v97, v112, v97, 1.0
	v_div_scale_f32 v112, s[36:37], v96, v96, 1.0
	v_rcp_f32_e32 v113, v112
	s_nop 0
	v_fma_f32 v114, -v112, v113, 1.0
	v_fmac_f32_e32 v113, v114, v113
	v_div_scale_f32 v114, vcc, 1.0, v96, 1.0
	v_mul_f32_e32 v115, v114, v113
	v_fma_f32 v116, -v112, v115, v114
	v_fmac_f32_e32 v115, v116, v113
	v_fma_f32 v112, -v112, v115, v114
	v_div_fmas_f32 v112, v112, v113, v115
	v_div_fixup_f32 v96, v112, v96, 1.0
	v_cvt_pk_bf16_f32 v112, v96, v97
	v_mul_f32_e32 v96, 0xbfb8aa3b, v98
	v_mul_f32_e32 v97, 0xbfb8aa3b, v99
	v_exp_f32_e32 v96, v96
	v_exp_f32_e32 v97, v97
	s_nop 0
	v_pk_add_f32 v[96:97], v[96:97], 1.0 op_sel_hi:[1,0]
	s_nop 0
	v_div_scale_f32 v98, s[36:37], v97, v97, 1.0
	v_rcp_f32_e32 v99, v98
	s_nop 0
	v_fma_f32 v113, -v98, v99, 1.0
	v_fmac_f32_e32 v99, v113, v99
	v_div_scale_f32 v113, vcc, 1.0, v97, 1.0
	v_mul_f32_e32 v114, v113, v99
	v_fma_f32 v115, -v98, v114, v113
	v_fmac_f32_e32 v114, v115, v99
	v_fma_f32 v98, -v98, v114, v113
	v_div_fmas_f32 v98, v98, v99, v114
	v_div_fixup_f32 v97, v98, v97, 1.0
	v_div_scale_f32 v98, s[36:37], v96, v96, 1.0
	v_rcp_f32_e32 v99, v98
	s_nop 0
	v_fma_f32 v113, -v98, v99, 1.0
	v_fmac_f32_e32 v99, v113, v99
	v_div_scale_f32 v113, vcc, 1.0, v96, 1.0
	v_mul_f32_e32 v114, v113, v99
	v_fma_f32 v115, -v98, v114, v113
	v_fmac_f32_e32 v114, v115, v99
	v_fma_f32 v98, -v98, v114, v113
	v_div_fmas_f32 v98, v98, v99, v114
	v_div_fixup_f32 v96, v98, v96, 1.0
	v_cvt_pk_bf16_f32 v96, v96, v97
	ds_write2st64_b32 v248, v112, v96 offset0:180 offset1:184
	v_mul_f32_e32 v96, 0xbfb8aa3b, v100
	v_mul_f32_e32 v97, 0xbfb8aa3b, v101
	v_exp_f32_e32 v96, v96
	v_exp_f32_e32 v97, v97
	s_nop 0
	v_pk_add_f32 v[96:97], v[96:97], 1.0 op_sel_hi:[1,0]
	s_nop 0
	v_div_scale_f32 v98, s[36:37], v97, v97, 1.0
	v_rcp_f32_e32 v99, v98
	s_nop 0
	v_fma_f32 v100, -v98, v99, 1.0
	v_fmac_f32_e32 v99, v100, v99
	v_div_scale_f32 v100, vcc, 1.0, v97, 1.0
	v_mul_f32_e32 v101, v100, v99
	v_fma_f32 v112, -v98, v101, v100
	v_fmac_f32_e32 v101, v112, v99
	v_fma_f32 v98, -v98, v101, v100
	v_div_fmas_f32 v98, v98, v99, v101
	v_div_fixup_f32 v97, v98, v97, 1.0
	v_div_scale_f32 v98, s[36:37], v96, v96, 1.0
	v_rcp_f32_e32 v99, v98
	s_nop 0
	v_fma_f32 v100, -v98, v99, 1.0
	v_fmac_f32_e32 v99, v100, v99
	v_div_scale_f32 v100, vcc, 1.0, v96, 1.0
	v_mul_f32_e32 v101, v100, v99
	v_fma_f32 v112, -v98, v101, v100
	v_fmac_f32_e32 v101, v112, v99
	v_fma_f32 v98, -v98, v101, v100
	v_div_fmas_f32 v98, v98, v99, v101
	v_div_fixup_f32 v96, v98, v96, 1.0
	v_cvt_pk_bf16_f32 v98, v96, v97
	v_mul_f32_e32 v96, 0xbfb8aa3b, v102
	v_mul_f32_e32 v97, 0xbfb8aa3b, v103
	v_exp_f32_e32 v96, v96
	v_exp_f32_e32 v97, v97
	s_nop 0
	v_pk_add_f32 v[96:97], v[96:97], 1.0 op_sel_hi:[1,0]
	s_nop 0
	v_div_scale_f32 v99, s[36:37], v97, v97, 1.0
	v_rcp_f32_e32 v100, v99
	s_nop 0
	v_fma_f32 v101, -v99, v100, 1.0
	v_fmac_f32_e32 v100, v101, v100
	v_div_scale_f32 v101, vcc, 1.0, v97, 1.0
	v_mul_f32_e32 v102, v101, v100
	v_fma_f32 v103, -v99, v102, v101
	v_fmac_f32_e32 v102, v103, v100
	v_fma_f32 v99, -v99, v102, v101
	v_div_fmas_f32 v99, v99, v100, v102
	v_div_fixup_f32 v97, v99, v97, 1.0
	v_div_scale_f32 v99, s[36:37], v96, v96, 1.0
	v_rcp_f32_e32 v100, v99
	s_nop 0
	v_fma_f32 v101, -v99, v100, 1.0
	v_fmac_f32_e32 v100, v101, v100
	v_div_scale_f32 v101, vcc, 1.0, v96, 1.0
	v_mul_f32_e32 v102, v101, v100
	v_fma_f32 v103, -v99, v102, v101
	v_fmac_f32_e32 v102, v103, v100
	v_fma_f32 v99, -v99, v102, v101
	v_div_fmas_f32 v99, v99, v100, v102
	v_div_fixup_f32 v96, v99, v96, 1.0
	v_cvt_pk_bf16_f32 v96, v96, v97
	ds_write2st64_b32 v248, v98, v96 offset0:188 offset1:192
	v_mul_f32_e32 v96, 0xbfb8aa3b, v104
	v_mul_f32_e32 v97, 0xbfb8aa3b, v105
	v_exp_f32_e32 v96, v96
	v_exp_f32_e32 v97, v97
	s_nop 0
	v_pk_add_f32 v[96:97], v[96:97], 1.0 op_sel_hi:[1,0]
	s_nop 0
	v_div_scale_f32 v98, s[36:37], v97, v97, 1.0
	v_rcp_f32_e32 v99, v98
	s_nop 0
	v_fma_f32 v100, -v98, v99, 1.0
	v_fmac_f32_e32 v99, v100, v99
	v_div_scale_f32 v100, vcc, 1.0, v97, 1.0
	v_mul_f32_e32 v101, v100, v99
	v_fma_f32 v102, -v98, v101, v100
; DEV float sigmoidf_(float x) { return 1.0f / (1.0f + __expf(-x)); }
; DEV void phase_p5(const Params& p, int l, unsigned char* smem) {
;     ...
; #pragma unroll
;       for (int a_ = 0; a_ < 2; ++a_)
; #pragma unroll
;         for (int b_ = 0; b_ < 2; ++b_) {
; #pragma unroll
;           for (int r = 0; r < 8; ++r)
;             sG[((a_ * 2 + b_) * 8 + r) * 256 + tid] = pk2bf(sigmoidf_(g[a_][2 + b_][2 * r]), sigmoidf_(g[a_][2 + b_][2 * r + 1]));
;           __builtin_amdgcn_sched_barrier(0);
;         }
	v_fmac_f32_e32 v101, v102, v99
	v_fma_f32 v98, -v98, v101, v100
	v_div_fmas_f32 v98, v98, v99, v101
	v_div_fixup_f32 v97, v98, v97, 1.0
	v_div_scale_f32 v98, s[36:37], v96, v96, 1.0
	v_rcp_f32_e32 v99, v98
	s_nop 0
	v_fma_f32 v100, -v98, v99, 1.0
	v_fmac_f32_e32 v99, v100, v99
	v_div_scale_f32 v100, vcc, 1.0, v96, 1.0
	v_mul_f32_e32 v101, v100, v99
	v_fma_f32 v102, -v98, v101, v100
	v_fmac_f32_e32 v101, v102, v99
	v_fma_f32 v98, -v98, v101, v100
	v_div_fmas_f32 v98, v98, v99, v101
	v_div_fixup_f32 v96, v98, v96, 1.0
	v_cvt_pk_bf16_f32 v98, v96, v97
	v_mul_f32_e32 v96, 0xbfb8aa3b, v106
	v_mul_f32_e32 v97, 0xbfb8aa3b, v107
	v_exp_f32_e32 v96, v96
	v_exp_f32_e32 v97, v97
	s_nop 0
	v_pk_add_f32 v[96:97], v[96:97], 1.0 op_sel_hi:[1,0]
	s_nop 0
	v_div_scale_f32 v99, s[36:37], v97, v97, 1.0
	v_rcp_f32_e32 v100, v99
	s_nop 0
	v_fma_f32 v101, -v99, v100, 1.0
	v_fmac_f32_e32 v100, v101, v100
	v_div_scale_f32 v101, vcc, 1.0, v97, 1.0
	v_mul_f32_e32 v102, v101, v100
	v_fma_f32 v103, -v99, v102, v101
	v_fmac_f32_e32 v102, v103, v100
	v_fma_f32 v99, -v99, v102, v101
	v_div_fmas_f32 v99, v99, v100, v102
	v_div_fixup_f32 v97, v99, v97, 1.0
	v_div_scale_f32 v99, s[36:37], v96, v96, 1.0
	v_rcp_f32_e32 v100, v99
	s_nop 0
	v_fma_f32 v101, -v99, v100, 1.0
	v_fmac_f32_e32 v100, v101, v100
	v_div_scale_f32 v101, vcc, 1.0, v96, 1.0
	v_mul_f32_e32 v102, v101, v100
	v_fma_f32 v103, -v99, v102, v101
	v_fmac_f32_e32 v102, v103, v100
	v_fma_f32 v99, -v99, v102, v101
	v_div_fmas_f32 v99, v99, v100, v102
	v_div_fixup_f32 v96, v99, v96, 1.0
	v_cvt_pk_bf16_f32 v96, v96, v97
	ds_write2st64_b32 v248, v98, v96 offset0:196 offset1:200
	v_mul_f32_e32 v96, 0xbfb8aa3b, v108
	v_mul_f32_e32 v97, 0xbfb8aa3b, v109
	v_exp_f32_e32 v96, v96
	v_exp_f32_e32 v97, v97
	s_nop 0
	v_pk_add_f32 v[96:97], v[96:97], 1.0 op_sel_hi:[1,0]
	s_nop 0
	v_div_scale_f32 v98, s[36:37], v97, v97, 1.0
	v_rcp_f32_e32 v99, v98
	s_nop 0
	v_fma_f32 v100, -v98, v99, 1.0
	v_fmac_f32_e32 v99, v100, v99
	v_div_scale_f32 v100, vcc, 1.0, v97, 1.0
	v_mul_f32_e32 v101, v100, v99
	v_fma_f32 v102, -v98, v101, v100
	v_fmac_f32_e32 v101, v102, v99
	v_fma_f32 v98, -v98, v101, v100
	v_div_fmas_f32 v98, v98, v99, v101
	v_div_fixup_f32 v97, v98, v97, 1.0
	v_div_scale_f32 v98, s[36:37], v96, v96, 1.0
	v_rcp_f32_e32 v99, v98
	s_nop 0
	v_fma_f32 v100, -v98, v99, 1.0
	v_fmac_f32_e32 v99, v100, v99
	v_div_scale_f32 v100, vcc, 1.0, v96, 1.0
	v_mul_f32_e32 v101, v100, v99
	v_fma_f32 v102, -v98, v101, v100
	v_fmac_f32_e32 v101, v102, v99
	v_fma_f32 v98, -v98, v101, v100
	v_div_fmas_f32 v98, v98, v99, v101
	v_div_fixup_f32 v96, v98, v96, 1.0
	v_cvt_pk_bf16_f32 v98, v96, v97
	v_mul_f32_e32 v96, 0xbfb8aa3b, v110
	v_mul_f32_e32 v97, 0xbfb8aa3b, v111
	v_exp_f32_e32 v96, v96
	v_exp_f32_e32 v97, v97
	s_nop 0
	v_pk_add_f32 v[96:97], v[96:97], 1.0 op_sel_hi:[1,0]
	s_nop 0
	v_div_scale_f32 v99, s[36:37], v97, v97, 1.0
	v_rcp_f32_e32 v100, v99
	s_nop 0
	v_fma_f32 v101, -v99, v100, 1.0
	v_fmac_f32_e32 v100, v101, v100
	v_div_scale_f32 v101, vcc, 1.0, v97, 1.0
	v_mul_f32_e32 v102, v101, v100
	v_fma_f32 v103, -v99, v102, v101
	v_fmac_f32_e32 v102, v103, v100
	v_fma_f32 v99, -v99, v102, v101
	v_div_fmas_f32 v99, v99, v100, v102
	v_div_fixup_f32 v97, v99, v97, 1.0
	v_div_scale_f32 v99, s[36:37], v96, v96, 1.0
	v_rcp_f32_e32 v100, v99
	s_nop 0
	v_fma_f32 v101, -v99, v100, 1.0
	v_fmac_f32_e32 v100, v101, v100
	v_div_scale_f32 v101, vcc, 1.0, v96, 1.0
	v_mul_f32_e32 v102, v101, v100
	v_fma_f32 v103, -v99, v102, v101
	v_fmac_f32_e32 v102, v103, v100
	v_fma_f32 v99, -v99, v102, v101
	v_div_fmas_f32 v99, v99, v100, v102
	v_div_fixup_f32 v96, v99, v96, 1.0
	v_cvt_pk_bf16_f32 v96, v96, v97
	ds_write2st64_b32 v248, v98, v96 offset0:204 offset1:208
	v_mul_f32_e32 v80, 0xbfb8aa3b, v80
	v_mul_f32_e32 v81, 0xbfb8aa3b, v81
	v_exp_f32_e32 v80, v80
	v_exp_f32_e32 v81, v81
	s_nop 0
	v_pk_add_f32 v[80:81], v[80:81], 1.0 op_sel_hi:[1,0]
	s_nop 0
	v_div_scale_f32 v96, s[36:37], v81, v81, 1.0
	v_rcp_f32_e32 v97, v96
	s_nop 0
	v_fma_f32 v98, -v96, v97, 1.0
	v_fmac_f32_e32 v97, v98, v97
	v_div_scale_f32 v98, vcc, 1.0, v81, 1.0
	v_mul_f32_e32 v99, v98, v97
	v_fma_f32 v100, -v96, v99, v98
	v_fmac_f32_e32 v99, v100, v97
	v_fma_f32 v96, -v96, v99, v98
	v_div_fmas_f32 v96, v96, v97, v99
	v_div_fixup_f32 v81, v96, v81, 1.0
	v_div_scale_f32 v96, s[36:37], v80, v80, 1.0
	v_rcp_f32_e32 v97, v96
	s_nop 0
	v_fma_f32 v98, -v96, v97, 1.0
	v_fmac_f32_e32 v97, v98, v97
	v_div_scale_f32 v98, vcc, 1.0, v80, 1.0
	v_mul_f32_e32 v99, v98, v97
	v_fma_f32 v100, -v96, v99, v98
	v_fmac_f32_e32 v99, v100, v97
	v_fma_f32 v96, -v96, v99, v98
	v_div_fmas_f32 v96, v96, v97, v99
	v_div_fixup_f32 v80, v96, v80, 1.0
	v_cvt_pk_bf16_f32 v96, v80, v81
	v_mul_f32_e32 v80, 0xbfb8aa3b, v82
	v_mul_f32_e32 v81, 0xbfb8aa3b, v83
	v_exp_f32_e32 v80, v80
	v_exp_f32_e32 v81, v81
	s_nop 0
	v_pk_add_f32 v[80:81], v[80:81], 1.0 op_sel_hi:[1,0]
	s_nop 0
	v_div_scale_f32 v82, s[36:37], v81, v81, 1.0
	v_rcp_f32_e32 v83, v82
	s_nop 0
	v_fma_f32 v97, -v82, v83, 1.0
	v_fmac_f32_e32 v83, v97, v83
	v_div_scale_f32 v97, vcc, 1.0, v81, 1.0
	v_mul_f32_e32 v98, v97, v83
	v_fma_f32 v99, -v82, v98, v97
	v_fmac_f32_e32 v98, v99, v83
	v_fma_f32 v82, -v82, v98, v97
	v_div_fmas_f32 v82, v82, v83, v98
	v_div_fixup_f32 v81, v82, v81, 1.0
	v_div_scale_f32 v82, s[36:37], v80, v80, 1.0
	v_rcp_f32_e32 v83, v82
	s_nop 0
	v_fma_f32 v97, -v82, v83, 1.0
	v_fmac_f32_e32 v83, v97, v83
	v_div_scale_f32 v97, vcc, 1.0, v80, 1.0
	v_mul_f32_e32 v98, v97, v83
	v_fma_f32 v99, -v82, v98, v97
	v_fmac_f32_e32 v98, v99, v83
	v_fma_f32 v82, -v82, v98, v97
	v_div_fmas_f32 v82, v82, v83, v98
	v_div_fixup_f32 v80, v82, v80, 1.0
	v_cvt_pk_bf16_f32 v80, v80, v81
; DEV float sigmoidf_(float x) { return 1.0f / (1.0f + __expf(-x)); }
; DEV void phase_p5(const Params& p, int l, unsigned char* smem) {
;     ...
; #pragma unroll
;       for (int a_ = 0; a_ < 2; ++a_)
; #pragma unroll
;         for (int b_ = 0; b_ < 2; ++b_) {
; #pragma unroll
;           for (int r = 0; r < 8; ++r)
;             sG[((a_ * 2 + b_) * 8 + r) * 256 + tid] = pk2bf(sigmoidf_(g[a_][2 + b_][2 * r]), sigmoidf_(g[a_][2 + b_][2 * r + 1]));
;           __builtin_amdgcn_sched_barrier(0);
;         }
	ds_write2st64_b32 v248, v96, v80 offset0:212 offset1:216
	v_mul_f32_e32 v80, 0xbfb8aa3b, v84
	v_mul_f32_e32 v81, 0xbfb8aa3b, v85
	v_exp_f32_e32 v80, v80
	v_exp_f32_e32 v81, v81
	s_nop 0
	v_pk_add_f32 v[80:81], v[80:81], 1.0 op_sel_hi:[1,0]
	s_nop 0
	v_div_scale_f32 v82, s[36:37], v81, v81, 1.0
	v_rcp_f32_e32 v83, v82
	s_nop 0
	v_fma_f32 v84, -v82, v83, 1.0
	v_fmac_f32_e32 v83, v84, v83
	v_div_scale_f32 v84, vcc, 1.0, v81, 1.0
	v_mul_f32_e32 v85, v84, v83
	v_fma_f32 v96, -v82, v85, v84
	v_fmac_f32_e32 v85, v96, v83
	v_fma_f32 v82, -v82, v85, v84
	v_div_fmas_f32 v82, v82, v83, v85
	v_div_fixup_f32 v81, v82, v81, 1.0
	v_div_scale_f32 v82, s[36:37], v80, v80, 1.0
	v_rcp_f32_e32 v83, v82
	s_nop 0
	v_fma_f32 v84, -v82, v83, 1.0
	v_fmac_f32_e32 v83, v84, v83
	v_div_scale_f32 v84, vcc, 1.0, v80, 1.0
	v_mul_f32_e32 v85, v84, v83
	v_fma_f32 v96, -v82, v85, v84
	v_fmac_f32_e32 v85, v96, v83
	v_fma_f32 v82, -v82, v85, v84
	v_div_fmas_f32 v82, v82, v83, v85
	v_div_fixup_f32 v80, v82, v80, 1.0
	v_cvt_pk_bf16_f32 v82, v80, v81
	v_mul_f32_e32 v80, 0xbfb8aa3b, v86
	v_mul_f32_e32 v81, 0xbfb8aa3b, v87
	v_exp_f32_e32 v80, v80
	v_exp_f32_e32 v81, v81
	s_nop 0
	v_pk_add_f32 v[80:81], v[80:81], 1.0 op_sel_hi:[1,0]
	s_nop 0
	v_div_scale_f32 v83, s[36:37], v81, v81, 1.0
	v_rcp_f32_e32 v84, v83
	s_nop 0
	v_fma_f32 v85, -v83, v84, 1.0
	v_fmac_f32_e32 v84, v85, v84
	v_div_scale_f32 v85, vcc, 1.0, v81, 1.0
	v_mul_f32_e32 v86, v85, v84
	v_fma_f32 v87, -v83, v86, v85
	v_fmac_f32_e32 v86, v87, v84
	v_fma_f32 v83, -v83, v86, v85
	v_div_fmas_f32 v83, v83, v84, v86
	v_div_fixup_f32 v81, v83, v81, 1.0
	v_div_scale_f32 v83, s[36:37], v80, v80, 1.0
	v_rcp_f32_e32 v84, v83
	s_nop 0
	v_fma_f32 v85, -v83, v84, 1.0
	v_fmac_f32_e32 v84, v85, v84
	v_div_scale_f32 v85, vcc, 1.0, v80, 1.0
	v_mul_f32_e32 v86, v85, v84
	v_fma_f32 v87, -v83, v86, v85
	v_fmac_f32_e32 v86, v87, v84
	v_fma_f32 v83, -v83, v86, v85
	v_div_fmas_f32 v83, v83, v84, v86
	v_div_fixup_f32 v80, v83, v80, 1.0
	v_cvt_pk_bf16_f32 v80, v80, v81
	ds_write2st64_b32 v248, v82, v80 offset0:220 offset1:224
	v_mul_f32_e32 v80, 0xbfb8aa3b, v88
	v_mul_f32_e32 v81, 0xbfb8aa3b, v89
	v_exp_f32_e32 v80, v80
	v_exp_f32_e32 v81, v81
	s_nop 0
	v_pk_add_f32 v[80:81], v[80:81], 1.0 op_sel_hi:[1,0]
	s_nop 0
	v_div_scale_f32 v82, s[36:37], v81, v81, 1.0
	v_rcp_f32_e32 v83, v82
	s_nop 0
	v_fma_f32 v84, -v82, v83, 1.0
	v_fmac_f32_e32 v83, v84, v83
	v_div_scale_f32 v84, vcc, 1.0, v81, 1.0
	v_mul_f32_e32 v85, v84, v83
	v_fma_f32 v86, -v82, v85, v84
	v_fmac_f32_e32 v85, v86, v83
	v_fma_f32 v82, -v82, v85, v84
	v_div_fmas_f32 v82, v82, v83, v85
	v_div_fixup_f32 v81, v82, v81, 1.0
	v_div_scale_f32 v82, s[36:37], v80, v80, 1.0
	v_rcp_f32_e32 v83, v82
	s_nop 0
	v_fma_f32 v84, -v82, v83, 1.0
	v_fmac_f32_e32 v83, v84, v83
	v_div_scale_f32 v84, vcc, 1.0, v80, 1.0
	v_mul_f32_e32 v85, v84, v83
	v_fma_f32 v86, -v82, v85, v84
	v_fmac_f32_e32 v85, v86, v83
	v_fma_f32 v82, -v82, v85, v84
	v_div_fmas_f32 v82, v82, v83, v85
	v_div_fixup_f32 v80, v82, v80, 1.0
	v_cvt_pk_bf16_f32 v82, v80, v81
	v_mul_f32_e32 v80, 0xbfb8aa3b, v90
	v_mul_f32_e32 v81, 0xbfb8aa3b, v91
	v_exp_f32_e32 v80, v80
	v_exp_f32_e32 v81, v81
	s_nop 0
	v_pk_add_f32 v[80:81], v[80:81], 1.0 op_sel_hi:[1,0]
	s_nop 0
	v_div_scale_f32 v83, s[36:37], v81, v81, 1.0
	v_rcp_f32_e32 v84, v83
	s_nop 0
	v_fma_f32 v85, -v83, v84, 1.0
	v_fmac_f32_e32 v84, v85, v84
	v_div_scale_f32 v85, vcc, 1.0, v81, 1.0
	v_mul_f32_e32 v86, v85, v84
	v_fma_f32 v87, -v83, v86, v85
	v_fmac_f32_e32 v86, v87, v84
	v_fma_f32 v83, -v83, v86, v85
	v_div_fmas_f32 v83, v83, v84, v86
	v_div_fixup_f32 v81, v83, v81, 1.0
	v_div_scale_f32 v83, s[36:37], v80, v80, 1.0
	v_rcp_f32_e32 v84, v83
	s_nop 0
	v_fma_f32 v85, -v83, v84, 1.0
	v_fmac_f32_e32 v84, v85, v84
	v_div_scale_f32 v85, vcc, 1.0, v80, 1.0
	v_mul_f32_e32 v86, v85, v84
	v_fma_f32 v87, -v83, v86, v85
	v_fmac_f32_e32 v86, v87, v84
	v_fma_f32 v83, -v83, v86, v85
	v_div_fmas_f32 v83, v83, v84, v86
	v_div_fixup_f32 v80, v83, v80, 1.0
	v_cvt_pk_bf16_f32 v80, v80, v81
	ds_write2st64_b32 v248, v82, v80 offset0:228 offset1:232
	v_mul_f32_e32 v80, 0xbfb8aa3b, v92
	v_mul_f32_e32 v81, 0xbfb8aa3b, v93
	v_exp_f32_e32 v80, v80
	v_exp_f32_e32 v81, v81
	s_nop 0
	v_pk_add_f32 v[80:81], v[80:81], 1.0 op_sel_hi:[1,0]
	s_nop 0
	v_div_scale_f32 v82, s[36:37], v81, v81, 1.0
	v_rcp_f32_e32 v83, v82
	s_nop 0
	v_fma_f32 v84, -v82, v83, 1.0
	v_fmac_f32_e32 v83, v84, v83
	v_div_scale_f32 v84, vcc, 1.0, v81, 1.0
	v_mul_f32_e32 v85, v84, v83
	v_fma_f32 v86, -v82, v85, v84
	v_fmac_f32_e32 v85, v86, v83
	v_fma_f32 v82, -v82, v85, v84
	v_div_fmas_f32 v82, v82, v83, v85
	v_div_fixup_f32 v81, v82, v81, 1.0
	v_div_scale_f32 v82, s[36:37], v80, v80, 1.0
	v_rcp_f32_e32 v83, v82
	s_nop 0
	v_fma_f32 v84, -v82, v83, 1.0
	v_fmac_f32_e32 v83, v84, v83
	v_div_scale_f32 v84, vcc, 1.0, v80, 1.0
	v_mul_f32_e32 v85, v84, v83
	v_fma_f32 v86, -v82, v85, v84
	v_fmac_f32_e32 v85, v86, v83
	v_fma_f32 v82, -v82, v85, v84
	v_div_fmas_f32 v82, v82, v83, v85
	v_div_fixup_f32 v80, v82, v80, 1.0
	v_cvt_pk_bf16_f32 v82, v80, v81
	v_mul_f32_e32 v80, 0xbfb8aa3b, v94
	v_mul_f32_e32 v81, 0xbfb8aa3b, v95
	v_exp_f32_e32 v80, v80
	v_exp_f32_e32 v81, v81
	s_nop 0
	v_pk_add_f32 v[80:81], v[80:81], 1.0 op_sel_hi:[1,0]
	s_nop 0
	v_div_scale_f32 v83, s[36:37], v81, v81, 1.0
	v_rcp_f32_e32 v84, v83
	s_nop 0
	v_fma_f32 v85, -v83, v84, 1.0
	v_fmac_f32_e32 v84, v85, v84
	v_div_scale_f32 v85, vcc, 1.0, v81, 1.0
	v_mul_f32_e32 v86, v85, v84
	v_fma_f32 v87, -v83, v86, v85
	v_fmac_f32_e32 v86, v87, v84
	v_fma_f32 v83, -v83, v86, v85
	v_div_fmas_f32 v83, v83, v84, v86
	v_div_fixup_f32 v81, v83, v81, 1.0
	v_div_scale_f32 v83, s[36:37], v80, v80, 1.0
; DEV float sigmoidf_(float x) { return 1.0f / (1.0f + __expf(-x)); }
; DEV void phase_p5(const Params& p, int l, unsigned char* smem) {
;     ...
; #pragma unroll
;       for (int a_ = 0; a_ < 2; ++a_)
; #pragma unroll
;         for (int b_ = 0; b_ < 2; ++b_) {
; #pragma unroll
;           for (int r = 0; r < 8; ++r)
;             sG[((a_ * 2 + b_) * 8 + r) * 256 + tid] = pk2bf(sigmoidf_(g[a_][2 + b_][2 * r]), sigmoidf_(g[a_][2 + b_][2 * r + 1]));
;           __builtin_amdgcn_sched_barrier(0);
;         }
	v_rcp_f32_e32 v84, v83
	s_nop 0
	v_fma_f32 v85, -v83, v84, 1.0
	v_fmac_f32_e32 v84, v85, v84
	v_div_scale_f32 v85, vcc, 1.0, v80, 1.0
	v_mul_f32_e32 v86, v85, v84
	v_fma_f32 v87, -v83, v86, v85
	v_fmac_f32_e32 v86, v87, v84
	v_fma_f32 v83, -v83, v86, v85
	v_div_fmas_f32 v83, v83, v84, v86
	v_div_fixup_f32 v80, v83, v80, 1.0
	v_cvt_pk_bf16_f32 v80, v80, v81
	ds_write2st64_b32 v248, v82, v80 offset0:236 offset1:240
	v_mul_f32_e32 v64, 0xbfb8aa3b, v64
	v_mul_f32_e32 v65, 0xbfb8aa3b, v65
	v_exp_f32_e32 v64, v64
	v_exp_f32_e32 v65, v65
	s_nop 0
	v_pk_add_f32 v[64:65], v[64:65], 1.0 op_sel_hi:[1,0]
	s_nop 0
	v_div_scale_f32 v80, s[36:37], v65, v65, 1.0
	v_rcp_f32_e32 v81, v80
	s_nop 0
	v_fma_f32 v82, -v80, v81, 1.0
	v_fmac_f32_e32 v81, v82, v81
	v_div_scale_f32 v82, vcc, 1.0, v65, 1.0
	v_mul_f32_e32 v83, v82, v81
	v_fma_f32 v84, -v80, v83, v82
	v_fmac_f32_e32 v83, v84, v81
	v_fma_f32 v80, -v80, v83, v82
	v_div_fmas_f32 v80, v80, v81, v83
	v_div_fixup_f32 v65, v80, v65, 1.0
	v_div_scale_f32 v80, s[36:37], v64, v64, 1.0
	v_rcp_f32_e32 v81, v80
	s_nop 0
	v_fma_f32 v82, -v80, v81, 1.0
	v_fmac_f32_e32 v81, v82, v81
	v_div_scale_f32 v82, vcc, 1.0, v64, 1.0
	v_mul_f32_e32 v83, v82, v81
	v_fma_f32 v84, -v80, v83, v82
	v_fmac_f32_e32 v83, v84, v81
	v_fma_f32 v80, -v80, v83, v82
	v_div_fmas_f32 v80, v80, v81, v83
	v_div_fixup_f32 v64, v80, v64, 1.0
	v_cvt_pk_bf16_f32 v80, v64, v65
	v_mul_f32_e32 v64, 0xbfb8aa3b, v66
	v_mul_f32_e32 v65, 0xbfb8aa3b, v67
	v_exp_f32_e32 v64, v64
	v_exp_f32_e32 v65, v65
	s_nop 0
	v_pk_add_f32 v[64:65], v[64:65], 1.0 op_sel_hi:[1,0]
	s_nop 0
	v_div_scale_f32 v66, s[36:37], v65, v65, 1.0
	v_rcp_f32_e32 v67, v66
	s_nop 0
	v_fma_f32 v81, -v66, v67, 1.0
	v_fmac_f32_e32 v67, v81, v67
	v_div_scale_f32 v81, vcc, 1.0, v65, 1.0
	v_mul_f32_e32 v82, v81, v67
	v_fma_f32 v83, -v66, v82, v81
	v_fmac_f32_e32 v82, v83, v67
	v_fma_f32 v66, -v66, v82, v81
	v_div_fmas_f32 v66, v66, v67, v82
	v_div_fixup_f32 v65, v66, v65, 1.0
	v_div_scale_f32 v66, s[36:37], v64, v64, 1.0
	v_rcp_f32_e32 v67, v66
	s_nop 0
	v_fma_f32 v81, -v66, v67, 1.0
	v_fmac_f32_e32 v67, v81, v67
	v_div_scale_f32 v81, vcc, 1.0, v64, 1.0
	v_mul_f32_e32 v82, v81, v67
	v_fma_f32 v83, -v66, v82, v81
	v_fmac_f32_e32 v82, v83, v67
	v_fma_f32 v66, -v66, v82, v81
	v_div_fmas_f32 v66, v66, v67, v82
	v_div_fixup_f32 v64, v66, v64, 1.0
	v_cvt_pk_bf16_f32 v64, v64, v65
	ds_write2st64_b32 v248, v80, v64 offset0:244 offset1:248
	v_mul_f32_e32 v64, 0xbfb8aa3b, v68
	v_mul_f32_e32 v65, 0xbfb8aa3b, v69
	v_exp_f32_e32 v64, v64
	v_exp_f32_e32 v65, v65
	s_nop 0
	v_pk_add_f32 v[64:65], v[64:65], 1.0 op_sel_hi:[1,0]
	s_nop 0
	v_div_scale_f32 v66, s[36:37], v65, v65, 1.0
	v_rcp_f32_e32 v67, v66
	s_nop 0
	v_fma_f32 v68, -v66, v67, 1.0
	v_fmac_f32_e32 v67, v68, v67
	v_div_scale_f32 v68, vcc, 1.0, v65, 1.0
	v_mul_f32_e32 v69, v68, v67
	v_fma_f32 v80, -v66, v69, v68
	v_fmac_f32_e32 v69, v80, v67
	v_fma_f32 v66, -v66, v69, v68
	v_div_fmas_f32 v66, v66, v67, v69
	v_div_fixup_f32 v65, v66, v65, 1.0
	v_div_scale_f32 v66, s[36:37], v64, v64, 1.0
	v_rcp_f32_e32 v67, v66
	s_nop 0
	v_fma_f32 v68, -v66, v67, 1.0
	v_fmac_f32_e32 v67, v68, v67
	v_div_scale_f32 v68, vcc, 1.0, v64, 1.0
	v_mul_f32_e32 v69, v68, v67
	v_fma_f32 v80, -v66, v69, v68
	v_fmac_f32_e32 v69, v80, v67
	v_fma_f32 v66, -v66, v69, v68
	v_div_fmas_f32 v66, v66, v67, v69
	v_div_fixup_f32 v64, v66, v64, 1.0
	v_cvt_pk_bf16_f32 v64, v64, v65
	ds_write_b32 v248, v64 offset:64512
	v_mul_f32_e32 v64, 0xbfb8aa3b, v70
	v_mul_f32_e32 v65, 0xbfb8aa3b, v71
	v_exp_f32_e32 v64, v64
	v_exp_f32_e32 v65, v65
	s_nop 0
	v_pk_add_f32 v[64:65], v[64:65], 1.0 op_sel_hi:[1,0]
	s_nop 0
	v_div_scale_f32 v66, s[36:37], v65, v65, 1.0
	v_rcp_f32_e32 v67, v66
	s_nop 0
	v_fma_f32 v68, -v66, v67, 1.0
	v_fmac_f32_e32 v67, v68, v67
	v_div_scale_f32 v68, vcc, 1.0, v65, 1.0
	v_mul_f32_e32 v69, v68, v67
	v_fma_f32 v70, -v66, v69, v68
	v_fmac_f32_e32 v69, v70, v67
	v_fma_f32 v66, -v66, v69, v68
	v_div_fmas_f32 v66, v66, v67, v69
	v_div_fixup_f32 v65, v66, v65, 1.0
	v_div_scale_f32 v66, s[36:37], v64, v64, 1.0
	v_rcp_f32_e32 v67, v66
	s_nop 0
	v_fma_f32 v68, -v66, v67, 1.0
	v_fmac_f32_e32 v67, v68, v67
	v_div_scale_f32 v68, vcc, 1.0, v64, 1.0
	v_mul_f32_e32 v69, v68, v67
	v_fma_f32 v70, -v66, v69, v68
	v_fmac_f32_e32 v69, v70, v67
	v_fma_f32 v66, -v66, v69, v68
	v_div_fmas_f32 v66, v66, v67, v69
	v_div_fixup_f32 v64, v66, v64, 1.0
	v_cvt_pk_bf16_f32 v66, v64, v65
	v_mul_f32_e32 v64, 0xbfb8aa3b, v72
	v_mul_f32_e32 v65, 0xbfb8aa3b, v73
	v_exp_f32_e32 v64, v64
	v_exp_f32_e32 v65, v65
	s_nop 0
	v_pk_add_f32 v[64:65], v[64:65], 1.0 op_sel_hi:[1,0]
	s_nop 0
	v_div_scale_f32 v67, s[36:37], v65, v65, 1.0
	v_rcp_f32_e32 v68, v67
	s_nop 0
	v_fma_f32 v69, -v67, v68, 1.0
	v_fmac_f32_e32 v68, v69, v68
	v_div_scale_f32 v69, vcc, 1.0, v65, 1.0
	v_mul_f32_e32 v70, v69, v68
	v_fma_f32 v71, -v67, v70, v69
	v_fmac_f32_e32 v70, v71, v68
	v_fma_f32 v67, -v67, v70, v69
	v_div_fmas_f32 v67, v67, v68, v70
	v_div_fixup_f32 v65, v67, v65, 1.0
	v_div_scale_f32 v67, s[36:37], v64, v64, 1.0
	v_rcp_f32_e32 v68, v67
	s_nop 0
	v_fma_f32 v69, -v67, v68, 1.0
	v_fmac_f32_e32 v68, v69, v68
	v_div_scale_f32 v69, vcc, 1.0, v64, 1.0
	v_mul_f32_e32 v70, v69, v68
	v_fma_f32 v71, -v67, v70, v69
	v_fmac_f32_e32 v70, v71, v68
	v_fma_f32 v67, -v67, v70, v69
	v_div_fmas_f32 v67, v67, v68, v70
	v_div_fixup_f32 v64, v67, v64, 1.0
	v_cvt_pk_bf16_f32 v64, v64, v65
	ds_write2st64_b32 v249, v66, v64 offset0:108 offset1:112
	v_mul_f32_e32 v64, 0xbfb8aa3b, v74
	v_mul_f32_e32 v65, 0xbfb8aa3b, v75
	v_exp_f32_e32 v64, v64
	v_exp_f32_e32 v65, v65
	s_nop 0
	v_pk_add_f32 v[64:65], v[64:65], 1.0 op_sel_hi:[1,0]
	s_nop 0
; DEV float sigmoidf_(float x) { return 1.0f / (1.0f + __expf(-x)); }
;     ...
;   const int srow = tid >> 3, scol = (tid & 7) * 8;
;   const u16* ap = A + (size_t)srow * lda + scol;
;   const u16* bp = B + (size_t)srow * ldb + scol;
;   bf16x8 ra[DEPTH][4], rb[DEPTH][4];
;   float ssq[4] = {0.f, 0.f, 0.f, 0.f};
;   const int nk = K >> 6;
; #pragma unroll
;   for (int d = 0; d < DEPTH; ++d)
; #pragma unroll
;     for (int i = 0; i < 4; ++i) {
;       ra[d][i] = *(const bf16x8*)(ap + d * 64 + (size_t)(32 * i) * lda);
;       rb[d][i] = *(const bf16x8*)(bp + d * 64 + (size_t)(32 * i) * ldb);
;     }
; DEV void phase_p5(const Params& p, int l, unsigned char* smem) {
;     ...
; #pragma unroll
;       for (int a_ = 0; a_ < 2; ++a_)
; #pragma unroll
;         for (int b_ = 0; b_ < 2; ++b_) {
; #pragma unroll
;           for (int r = 0; r < 8; ++r)
;             sG[((a_ * 2 + b_) * 8 + r) * 256 + tid] = pk2bf(sigmoidf_(g[a_][2 + b_][2 * r]), sigmoidf_(g[a_][2 + b_][2 * r + 1]));
;           __builtin_amdgcn_sched_barrier(0);
;         }
	v_div_scale_f32 v66, s[36:37], v65, v65, 1.0
	v_rcp_f32_e32 v67, v66
	s_nop 0
	v_fma_f32 v68, -v66, v67, 1.0
	v_fmac_f32_e32 v67, v68, v67
	v_div_scale_f32 v68, vcc, 1.0, v65, 1.0
	v_mul_f32_e32 v69, v68, v67
	v_fma_f32 v70, -v66, v69, v68
	v_fmac_f32_e32 v69, v70, v67
	v_fma_f32 v66, -v66, v69, v68
	v_div_fmas_f32 v66, v66, v67, v69
	v_div_fixup_f32 v65, v66, v65, 1.0
	v_div_scale_f32 v66, s[36:37], v64, v64, 1.0
	v_rcp_f32_e32 v67, v66
	s_nop 0
	v_fma_f32 v68, -v66, v67, 1.0
	v_fmac_f32_e32 v67, v68, v67
	v_div_scale_f32 v68, vcc, 1.0, v64, 1.0
	v_mul_f32_e32 v69, v68, v67
	v_fma_f32 v70, -v66, v69, v68
	v_fmac_f32_e32 v69, v70, v67
	v_fma_f32 v66, -v66, v69, v68
	v_div_fmas_f32 v66, v66, v67, v69
	v_div_fixup_f32 v64, v66, v64, 1.0
	v_cvt_pk_bf16_f32 v66, v64, v65
	v_mul_f32_e32 v64, 0xbfb8aa3b, v76
	v_mul_f32_e32 v65, 0xbfb8aa3b, v77
	v_exp_f32_e32 v64, v64
	v_exp_f32_e32 v65, v65
	s_nop 0
	v_pk_add_f32 v[64:65], v[64:65], 1.0 op_sel_hi:[1,0]
	s_nop 0
	v_div_scale_f32 v67, s[36:37], v65, v65, 1.0
	v_rcp_f32_e32 v68, v67
	s_nop 0
	v_fma_f32 v69, -v67, v68, 1.0
	v_fmac_f32_e32 v68, v69, v68
	v_div_scale_f32 v69, vcc, 1.0, v65, 1.0
	v_mul_f32_e32 v70, v69, v68
	v_fma_f32 v71, -v67, v70, v69
	v_fmac_f32_e32 v70, v71, v68
	v_fma_f32 v67, -v67, v70, v69
	v_div_fmas_f32 v67, v67, v68, v70
	v_div_fixup_f32 v65, v67, v65, 1.0
	v_div_scale_f32 v67, s[36:37], v64, v64, 1.0
	v_rcp_f32_e32 v68, v67
	s_nop 0
	v_fma_f32 v69, -v67, v68, 1.0
	v_fmac_f32_e32 v68, v69, v68
	v_div_scale_f32 v69, vcc, 1.0, v64, 1.0
	v_mul_f32_e32 v70, v69, v68
	v_fma_f32 v71, -v67, v70, v69
	v_fmac_f32_e32 v70, v71, v68
	v_fma_f32 v67, -v67, v70, v69
	v_div_fmas_f32 v67, v67, v68, v70
	v_div_fixup_f32 v64, v67, v64, 1.0
	v_cvt_pk_bf16_f32 v64, v64, v65
	ds_write2st64_b32 v249, v66, v64 offset0:116 offset1:120
	v_mul_f32_e32 v64, 0xbfb8aa3b, v78
	v_mul_f32_e32 v65, 0xbfb8aa3b, v79
	v_exp_f32_e32 v64, v64
	v_exp_f32_e32 v65, v65
	s_nop 0
	v_pk_add_f32 v[64:65], v[64:65], 1.0 op_sel_hi:[1,0]
	s_nop 0
	v_div_scale_f32 v66, s[36:37], v65, v65, 1.0
	v_rcp_f32_e32 v67, v66
	s_nop 0
	v_fma_f32 v68, -v66, v67, 1.0
	v_fmac_f32_e32 v67, v68, v67
	v_div_scale_f32 v68, vcc, 1.0, v65, 1.0
	v_mul_f32_e32 v69, v68, v67
	v_fma_f32 v70, -v66, v69, v68
	v_fmac_f32_e32 v69, v70, v67
	v_fma_f32 v66, -v66, v69, v68
	v_div_fmas_f32 v66, v66, v67, v69
	v_div_fixup_f32 v65, v66, v65, 1.0
	v_div_scale_f32 v66, s[36:37], v64, v64, 1.0
	v_rcp_f32_e32 v67, v66
	s_nop 0
	v_fma_f32 v68, -v66, v67, 1.0
	v_fmac_f32_e32 v67, v68, v67
	v_div_scale_f32 v68, vcc, 1.0, v64, 1.0
	v_mul_f32_e32 v69, v68, v67
	v_fma_f32 v70, -v66, v69, v68
	v_fmac_f32_e32 v69, v70, v67
	v_fma_f32 v66, -v66, v69, v68
	v_div_fmas_f32 v66, v66, v67, v69
	v_div_fixup_f32 v64, v66, v64, 1.0
	v_cvt_pk_bf16_f32 v64, v64, v65
	ds_write_b32 v249, v64 offset:31744
	v_mov_b32_e32 v90, v232
	s_lshl_b64 s[0:1], s[0:1], 1
	s_add_u32 s36, s8, s0
	v_ashrrev_i32_e32 v80, 3, v90
	v_ashrrev_i32_e32 v81, 31, v80
	s_addc_u32 s37, s9, s1
	s_lshl_b32 s20, s20, 1
	v_lshlrev_b64 v[64:65], 11, v[80:81]
	v_lshlrev_b32_e32 v68, 4, v90
	s_add_u32 s38, s14, s20
	v_lshl_add_u64 v[66:67], s[36:37], 0, v[64:65]
	v_and_b32_e32 v224, 0x70, v68
	s_addc_u32 s39, s15, 0
	v_lshl_add_u64 v[82:83], v[66:67], 0, v[224:225]
	v_lshl_add_u64 v[64:65], s[38:39], 0, v[64:65]
	v_add_co_u32_e32 v72, vcc, s35, v82
	v_lshl_add_u64 v[84:85], v[64:65], 0, v[224:225]
	s_nop 0
	v_addc_co_u32_e32 v73, vcc, 0, v83, vcc
	v_add_co_u32_e32 v76, vcc, s35, v84
	s_waitcnt vmcnt(0)
	v_mov_b32_e32 v64, v184
	v_mov_b32_e32 v65, v185
	v_mov_b32_e32 v66, v186
	v_mov_b32_e32 v67, v187
	v_mov_b32_e32 v68, v188
	v_mov_b32_e32 v69, v189
	v_mov_b32_e32 v70, v190
	v_mov_b32_e32 v71, v191
	v_addc_co_u32_e32 v77, vcc, 0, v85, vcc
	v_add_co_u32_e32 v86, vcc, s33, v82
	v_mov_b32_e32 v72, v192
	v_mov_b32_e32 v73, v193
	v_mov_b32_e32 v74, v194
	v_mov_b32_e32 v75, v195
	s_nop 0
	v_mov_b32_e32 v76, v196
	v_mov_b32_e32 v77, v197
	v_mov_b32_e32 v78, v198
	v_mov_b32_e32 v79, v199
	v_addc_co_u32_e32 v87, vcc, 0, v83, vcc
	v_add_co_u32_e32 v88, vcc, s33, v84
	s_waitcnt vmcnt(7)
	v_lshl_add_u64 v[160:161], v[82:83], 0, s[82:83]
	v_addc_co_u32_e32 v89, vcc, 0, v85, vcc
	v_mov_b32_e32 v96, v200
	v_mov_b32_e32 v97, v201
	v_mov_b32_e32 v98, v202
	v_mov_b32_e32 v99, v203
	v_mov_b32_e32 v100, v204
	v_mov_b32_e32 v101, v205
	v_mov_b32_e32 v102, v206
	v_mov_b32_e32 v103, v207
	v_add_co_u32_e32 v86, vcc, s40, v82
	v_lshl_add_u64 v[162:163], v[84:85], 0, s[82:83]
	s_nop 0
	v_addc_co_u32_e32 v87, vcc, 0, v83, vcc
	v_add_co_u32_e32 v88, vcc, s40, v84
	v_and_b32_e32 v82, 31, v90
	s_nop 0
	v_addc_co_u32_e32 v89, vcc, 0, v85, vcc
	v_mov_b32_e32 v104, v208
	v_mov_b32_e32 v105, v209
	v_mov_b32_e32 v106, v210
	v_mov_b32_e32 v107, v211
	v_mov_b32_e32 v108, v212
	v_mov_b32_e32 v109, v213
	v_mov_b32_e32 v110, v214
	v_mov_b32_e32 v111, v215
	v_lshrrev_b32_e32 v83, 2, v90
	v_lshrrev_b32_e32 v84, 1, v90
	v_and_b32_e32 v81, 64, v90
	v_mul_u32_u24_e32 v82, 0x48, v82
	v_and_b32_e32 v83, 8, v83
	v_and_b32_e32 v84, 0xfffffc0, v84
	v_add_lshl_u32 v82, v82, v83, 1
	s_waitcnt vmcnt(10)
	v_mad_u64_u32 v[164:165], s[36:37], v80, s49, v[224:225]
	v_mul_lo_u32 v83, v84, s49
	v_mul_u32_u24_e32 v81, 0x90, v81
	v_mov_b32_e32 v80, 0
	s_mov_b32 s21, 16
	v_add_u32_e32 v165, v82, v83
	v_add_u32_e32 v166, v82, v81
	v_mov_b32_e32 v81, v80
	v_mov_b32_e32 v82, v80
	v_mov_b32_e32 v83, v80
	v_mov_b32_e32 v84, v80
	v_mov_b32_e32 v85, v80
	v_mov_b32_e32 v86, v80
	v_mov_b32_e32 v87, v80
	v_mov_b32_e32 v88, v80
	v_mov_b32_e32 v89, v80
	v_mov_b32_e32 v90, v80
	v_mov_b32_e32 v91, v80
	v_mov_b32_e32 v92, v80
	v_mov_b32_e32 v93, v80
	v_mov_b32_e32 v94, v80
	v_mov_b32_e32 v95, v80
	v_mov_b32_e32 v112, v80
	v_mov_b32_e32 v113, v80
	v_mov_b32_e32 v114, v80
	v_mov_b32_e32 v115, v80
	v_mov_b32_e32 v116, v80
	v_mov_b32_e32 v117, v80
	v_mov_b32_e32 v118, v80
	v_mov_b32_e32 v119, v80
	v_mov_b32_e32 v120, v80
	v_mov_b32_e32 v121, v80
	v_mov_b32_e32 v122, v80
	v_mov_b32_e32 v123, v80
	v_mov_b32_e32 v124, v80
	v_mov_b32_e32 v125, v80
	v_mov_b32_e32 v126, v80
	v_mov_b32_e32 v127, v80
	v_mov_b32_e32 v128, v80
	v_mov_b32_e32 v129, v80
	v_mov_b32_e32 v130, v80
	v_mov_b32_e32 v131, v80
	v_mov_b32_e32 v132, v80
	v_mov_b32_e32 v133, v80
	v_mov_b32_e32 v134, v80
	v_mov_b32_e32 v135, v80
	v_mov_b32_e32 v136, v80
	v_mov_b32_e32 v137, v80
	v_mov_b32_e32 v138, v80
	v_mov_b32_e32 v139, v80
	v_mov_b32_e32 v140, v80
	v_mov_b32_e32 v141, v80
	v_mov_b32_e32 v142, v80
	v_mov_b32_e32 v143, v80
	v_mov_b32_e32 v144, v80
	v_mov_b32_e32 v145, v80
	v_mov_b32_e32 v146, v80
	v_mov_b32_e32 v147, v80
	v_mov_b32_e32 v148, v80
	v_mov_b32_e32 v149, v80
	v_mov_b32_e32 v150, v80
	v_mov_b32_e32 v151, v80
	v_mov_b32_e32 v152, v80
	v_mov_b32_e32 v153, v80
	v_mov_b32_e32 v154, v80
	v_mov_b32_e32 v155, v80
	v_mov_b32_e32 v156, v80
	v_mov_b32_e32 v157, v80
	v_mov_b32_e32 v158, v80
	v_mov_b32_e32 v159, v80
	s_branch .LBB0_1313
